# W_in natural GEMM: odd rounds take the neighbouring workgroup's tile (c^1) so every workgroup gets 3 sigmoid-epilogue tiles + 2 others instead of 5+0 / 1+4
# baseline (speedup 1.0000x reference)
.LBB0_408:
	s_add_i32 s61, s61, 1
	s_mul_i32 s36, s61, s27
	s_mul_hi_u32 s37, s61, s26
	s_add_i32 s37, s37, s36
	s_mul_i32 s36, s61, s26
	s_add_u32 s36, s36, s86
	s_addc_u32 s37, s37, s87
	s_and_b32 s100, s61, 1
	s_xor_b32 s36, s36, s100
	v_mov_b64_e32 v[2:3], 0x500
	v_cmp_lt_i64_e64 s[38:39], s[36:37], v[2:3]
	v_mov_b64_e32 v[2:3], 0x4ff
	v_cmp_gt_i64_e32 vcc, s[36:37], v[2:3]
	s_cbranch_vccnz .LBB0_410
	s_ashr_i32 s37, s36, 31
	s_lshr_b32 s37, s37, 29
	s_add_i32 s37, s36, s37
	s_ashr_i32 s41, s37, 3
	s_and_b32 s37, s37, -8
	s_sub_i32 s36, s36, s37
	s_cmp_lt_i32 s36, 0
	s_cselect_b32 s37, s97, 0xa0
	s_mul_i32 s36, s37, s36
	s_add_i32 s36, s36, s41
	s_mul_hi_i32 s37, s36, 0x66666667
	s_lshr_b32 s41, s37, 31
	s_ashr_i32 s37, s37, 7
	s_add_i32 s37, s37, s41
	s_lshl_b32 s41, s37, 3
	s_sub_i32 s42, 32, s41
	s_min_i32 s42, s42, 8
	s_abs_i32 s43, s42
	v_cvt_f32_u32_e32 v2, s43
	s_sub_i32 s45, 0, s43
	s_mulk_i32 s37, 0x140
	s_sub_i32 s36, s36, s37
	v_rcp_iflag_f32_e32 v2, v2
	s_abs_i32 s37, s36
	s_xor_b32 s44, s36, s42
	s_ashr_i32 s44, s44, 31
	v_mul_f32_e32 v2, 0x4f7ffffe, v2
	v_cvt_u32_f32_e32 v2, v2
	s_nop 0
	v_readfirstlane_b32 s46, v2
	s_mul_i32 s45, s45, s46
	s_mul_hi_u32 s45, s46, s45
	s_add_i32 s46, s46, s45
	s_mul_hi_u32 s45, s37, s46
	s_mul_i32 s46, s45, s43
	s_sub_i32 s37, s37, s46
	s_add_i32 s47, s45, 1
	s_sub_i32 s46, s37, s43
	s_cmp_ge_u32 s37, s43
	s_cselect_b32 s45, s47, s45
	s_cselect_b32 s37, s46, s37
	s_add_i32 s46, s45, 1
	s_cmp_ge_u32 s37, s43
	s_cselect_b32 s37, s46, s45
	s_xor_b32 s37, s37, s44
	s_sub_i32 s48, s37, s44
	s_mul_i32 s37, s48, s42
	s_sub_i32 s36, s36, s37
	s_add_i32 s50, s36, s41
